# plus first norm pass: adaLN vector loads issued before the x rows with one counted wait
# baseline (speedup 1.0000x reference)
.LBB0_138:
	v_ashrrev_i32_e32 v32, 13, v48
	v_ashrrev_i32_e32 v33, 12, v48
	v_add_u32_e32 v32, 16, v32
	v_ashrrev_i32_e32 v49, 31, v48
	v_cndmask_b32_e64 v32, v32, v33, s[8:9]
	v_lshlrev_b64 v[0:1], 12, v[48:49]
	v_add_u32_e32 v62, 1, v48
	v_mul_hi_i32_i24_e32 v33, 0x9000, v32
	v_mul_i32_i24_e32 v32, 0x9000, v32
	v_lshl_add_u64 v[0:1], v[50:51], 0, v[0:1]
	v_ashrrev_i32_e32 v63, 31, v62
	v_lshl_add_u64 v[32:33], s[68:69], 0, v[32:33]
	v_lshl_add_u64 v[76:77], v[32:33], 0, s[26:27]
	v_lshl_add_u64 v[92:93], v[32:33], 0, v[144:145]
	v_lshl_add_u64 v[128:129], v[76:77], 0, v[144:145]
	v_lshl_add_u64 v[130:131], v[76:77], 0, v[56:57]
	v_lshl_add_u64 v[132:133], v[76:77], 0, v[58:59]
	v_lshl_add_u64 v[134:135], v[76:77], 0, v[60:61]
	global_load_dwordx4 v[196:199], v[128:129], off
	global_load_dwordx4 v[200:203], v[130:131], off
	global_load_dwordx4 v[204:207], v[132:133], off
	global_load_dwordx4 v[208:211], v[134:135], off
	global_load_dwordx4 v[212:215], v[52:53], off
	global_load_dwordx4 v[216:219], v[52:53], off offset:1024
	global_load_dwordx4 v[220:223], v[52:53], off offset:2048
	global_load_dwordx4 v[224:227], v[52:53], off offset:3072
	global_load_dwordx4 v[32:35], v[92:93], off
	global_load_dwordx4 v[36:39], v[92:93], off offset:1024
	global_load_dwordx4 v[40:43], v[92:93], off offset:2048
	global_load_dwordx4 v[44:47], v[92:93], off offset:3072
	global_load_dwordx4 v[28:31], v[0:1], off nt
	global_load_dwordx4 v[24:27], v[0:1], off offset:1024 nt
	global_load_dwordx4 v[20:23], v[0:1], off offset:2048 nt
	global_load_dwordx4 v[16:19], v[0:1], off offset:3072 nt
	v_lshlrev_b64 v[0:1], 12, v[62:63]
	v_lshl_add_u64 v[0:1], v[50:51], 0, v[0:1]
	global_load_dwordx4 v[12:15], v[0:1], off nt
	global_load_dwordx4 v[8:11], v[0:1], off offset:1024 nt
	global_load_dwordx4 v[4:7], v[0:1], off offset:2048 nt
	s_nop 0
	global_load_dwordx4 v[0:3], v[0:1], off offset:3072 nt
	s_waitcnt vmcnt(8)
	v_pk_add_f32 v[196:197], v[196:197], 1.0 op_sel_hi:[1,0]
	v_pk_add_f32 v[198:199], v[198:199], 1.0 op_sel_hi:[1,0]
	v_pk_add_f32 v[200:201], v[200:201], 1.0 op_sel_hi:[1,0]
	v_pk_add_f32 v[202:203], v[202:203], 1.0 op_sel_hi:[1,0]
	v_pk_add_f32 v[204:205], v[204:205], 1.0 op_sel_hi:[1,0]
	v_pk_add_f32 v[206:207], v[206:207], 1.0 op_sel_hi:[1,0]
	v_pk_add_f32 v[208:209], v[208:209], 1.0 op_sel_hi:[1,0]
	v_pk_add_f32 v[210:211], v[210:211], 1.0 op_sel_hi:[1,0]
	v_pk_mul_f32 v[66:67], v[212:213], v[196:197]
	v_pk_mul_f32 v[64:65], v[214:215], v[198:199]
	v_pk_mul_f32 v[70:71], v[216:217], v[200:201]
	v_pk_mul_f32 v[68:69], v[218:219], v[202:203]
	v_pk_mul_f32 v[72:73], v[222:223], v[206:207]
	v_pk_mul_f32 v[74:75], v[220:221], v[204:205]
	v_pk_mul_f32 v[76:77], v[226:227], v[210:211]
	v_pk_mul_f32 v[78:79], v[224:225], v[208:209]
	s_waitcnt vmcnt(0)
	v_mov_b32_e32 v90, v29
	v_mov_b32_e32 v91, v25
	v_mov_b32_e32 v88, v28
	v_mov_b32_e32 v89, v24
	v_pk_mul_f32 v[90:91], v[90:91], v[90:91]
	v_mov_b32_e32 v92, v21
	v_pk_fma_f32 v[88:89], v[88:89], v[88:89], v[90:91]
	v_mov_b32_e32 v90, v30
	v_mov_b32_e32 v91, v26
	v_pk_fma_f32 v[88:89], v[90:91], v[90:91], v[88:89]
	v_mov_b32_e32 v90, v31
	v_mov_b32_e32 v91, v27
	v_mov_b32_e32 v93, v17
	v_pk_fma_f32 v[88:89], v[90:91], v[90:91], v[88:89]
	v_mov_b32_e32 v90, v20
	v_mov_b32_e32 v91, v16
	v_pk_mul_f32 v[92:93], v[92:93], v[92:93]
	v_add_f32_e32 v80, v88, v89
	v_pk_fma_f32 v[90:91], v[90:91], v[90:91], v[92:93]
	v_mov_b32_e32 v92, v22
	v_mov_b32_e32 v93, v18
	v_pk_fma_f32 v[90:91], v[92:93], v[92:93], v[90:91]
	v_mov_b32_e32 v92, v23
	v_mov_b32_e32 v93, v19
	v_pk_fma_f32 v[90:91], v[92:93], v[92:93], v[90:91]
	v_lshlrev_b64 v[88:89], 11, v[48:49]
	v_add_f32_e32 v80, v80, v90
	v_add_f32_e32 v80, v80, v91
	ds_bpermute_b32 v87, v81, v80
	v_add_u32_e32 v48, s95, v48
	s_waitcnt lgkmcnt(0)
	v_add_f32_e32 v80, v80, v87
	ds_bpermute_b32 v87, v82, v80
	s_waitcnt lgkmcnt(0)
	v_add_f32_e32 v80, v80, v87
	ds_bpermute_b32 v87, v83, v80
	s_waitcnt lgkmcnt(0)
	v_add_f32_e32 v80, v80, v87
	ds_bpermute_b32 v87, v84, v80
	s_waitcnt lgkmcnt(0)
	v_add_f32_e32 v80, v80, v87
	ds_bpermute_b32 v87, v85, v80
	s_waitcnt lgkmcnt(0)
	v_add_f32_e32 v80, v80, v87
	ds_bpermute_b32 v87, v86, v80
	s_waitcnt lgkmcnt(0)
	v_add_f32_e32 v80, v80, v87
	v_fmamk_f32 v80, v80, 0x3a800000, v146
	v_cmp_gt_f32_e32 vcc, s25, v80
	v_mul_f32_e32 v87, 0x4b800000, v80
	s_nop 0
	v_cndmask_b32_e32 v80, v80, v87, vcc
	v_rsq_f32_e32 v80, v80
	s_nop 0
	v_mul_f32_e32 v87, 0x45800000, v80
	v_cndmask_b32_e32 v80, v80, v87, vcc
	v_pk_mul_f32 v[28:29], v[28:29], v[80:81] op_sel_hi:[1,0]
	v_pk_mul_f32 v[30:31], v[30:31], v[80:81] op_sel_hi:[1,0]
	v_pk_fma_f32 v[28:29], v[66:67], v[28:29], v[32:33]
	v_pk_fma_f32 v[30:31], v[64:65], v[30:31], v[34:35]
	v_pk_mul_f32 v[24:25], v[24:25], v[80:81] op_sel_hi:[1,0]
	v_pk_mul_f32 v[20:21], v[20:21], v[80:81] op_sel_hi:[1,0]
	v_pk_mul_f32 v[16:17], v[16:17], v[80:81] op_sel_hi:[1,0]
	v_pk_mul_f32 v[18:19], v[18:19], v[80:81] op_sel_hi:[1,0]
	v_cvt_pk_bf16_f32 v28, v28, v29
	v_cvt_pk_bf16_f32 v29, v30, v31
	v_lshl_add_u64 v[30:31], v[54:55], 0, v[88:89]
	v_pk_mul_f32 v[26:27], v[26:27], v[80:81] op_sel_hi:[1,0]
	v_pk_fma_f32 v[24:25], v[70:71], v[24:25], v[36:37]
	v_pk_mul_f32 v[22:23], v[22:23], v[80:81] op_sel_hi:[1,0]
	v_pk_fma_f32 v[20:21], v[74:75], v[20:21], v[40:41]
	s_waitcnt vmcnt(0)
	v_pk_fma_f32 v[18:19], v[76:77], v[18:19], v[46:47]
	v_pk_fma_f32 v[16:17], v[78:79], v[16:17], v[44:45]
	global_store_dwordx2 v[30:31], v[28:29], off
	v_pk_fma_f32 v[26:27], v[68:69], v[26:27], v[38:39]
	v_cvt_pk_bf16_f32 v24, v24, v25
	v_pk_fma_f32 v[22:23], v[72:73], v[22:23], v[42:43]
	v_cvt_pk_bf16_f32 v25, v26, v27
	global_store_dwordx2 v[30:31], v[24:25], off offset:512
	v_cvt_pk_bf16_f32 v20, v20, v21
	v_cvt_pk_bf16_f32 v21, v22, v23
	global_store_dwordx2 v[30:31], v[20:21], off offset:1024
	v_cvt_pk_bf16_f32 v16, v16, v17
	v_cvt_pk_bf16_f32 v17, v18, v19
	v_mov_b32_e32 v18, v13
	v_mov_b32_e32 v19, v9
	global_store_dwordx2 v[30:31], v[16:17], off offset:1536
	v_mov_b32_e32 v16, v12
	v_mov_b32_e32 v17, v8
	v_pk_mul_f32 v[18:19], v[18:19], v[18:19]
	v_mov_b32_e32 v20, v5
	v_pk_fma_f32 v[16:17], v[16:17], v[16:17], v[18:19]
	v_mov_b32_e32 v18, v14
	v_mov_b32_e32 v19, v10
	v_pk_fma_f32 v[16:17], v[18:19], v[18:19], v[16:17]
	v_mov_b32_e32 v18, v15
	v_mov_b32_e32 v19, v11
	v_mov_b32_e32 v21, v1
	v_pk_fma_f32 v[16:17], v[18:19], v[18:19], v[16:17]
	v_mov_b32_e32 v18, v4
	v_mov_b32_e32 v19, v0
	v_pk_mul_f32 v[20:21], v[20:21], v[20:21]
	v_add_f32_e32 v16, v16, v17
	v_pk_fma_f32 v[18:19], v[18:19], v[18:19], v[20:21]
	v_mov_b32_e32 v20, v6
	v_mov_b32_e32 v21, v2
	v_pk_fma_f32 v[18:19], v[20:21], v[20:21], v[18:19]
	v_mov_b32_e32 v20, v7
	v_mov_b32_e32 v21, v3
	v_pk_fma_f32 v[18:19], v[20:21], v[20:21], v[18:19]
	s_nop 0
	v_add_f32_e32 v16, v16, v18
	v_add_f32_e32 v16, v16, v19
	ds_bpermute_b32 v17, v81, v16
	v_lshlrev_b64 v[18:19], 11, v[62:63]
	s_waitcnt lgkmcnt(0)
	v_add_f32_e32 v16, v16, v17
	ds_bpermute_b32 v17, v82, v16
	s_waitcnt lgkmcnt(0)
	v_add_f32_e32 v16, v16, v17
	ds_bpermute_b32 v17, v83, v16
	s_waitcnt lgkmcnt(0)
	v_add_f32_e32 v16, v16, v17
	ds_bpermute_b32 v17, v84, v16
	s_waitcnt lgkmcnt(0)
	v_add_f32_e32 v16, v16, v17
	ds_bpermute_b32 v17, v85, v16
	s_waitcnt lgkmcnt(0)
	v_add_f32_e32 v16, v16, v17
	ds_bpermute_b32 v17, v86, v16
	s_waitcnt lgkmcnt(0)
	v_add_f32_e32 v16, v16, v17
	v_fmamk_f32 v16, v16, 0x3a800000, v146
	v_cmp_gt_f32_e32 vcc, s25, v16
	v_mul_f32_e32 v17, 0x4b800000, v16
	s_nop 0
	v_cndmask_b32_e32 v16, v16, v17, vcc
	v_rsq_f32_e32 v16, v16
	s_nop 0
	v_mul_f32_e32 v17, 0x45800000, v16
	v_cndmask_b32_e32 v16, v16, v17, vcc
	v_pk_mul_f32 v[12:13], v[12:13], v[16:17] op_sel_hi:[1,0]
	v_pk_mul_f32 v[14:15], v[14:15], v[16:17] op_sel_hi:[1,0]
	v_pk_fma_f32 v[12:13], v[66:67], v[12:13], v[32:33]
	v_pk_fma_f32 v[14:15], v[64:65], v[14:15], v[34:35]
	v_pk_mul_f32 v[8:9], v[8:9], v[16:17] op_sel_hi:[1,0]
	v_pk_mul_f32 v[4:5], v[4:5], v[16:17] op_sel_hi:[1,0]
	v_pk_mul_f32 v[0:1], v[0:1], v[16:17] op_sel_hi:[1,0]
	v_cmp_lt_i32_e32 vcc, s19, v48
	v_cvt_pk_bf16_f32 v12, v12, v13
	v_cvt_pk_bf16_f32 v13, v14, v15
	v_lshl_add_u64 v[14:15], v[54:55], 0, v[18:19]
	v_pk_mul_f32 v[10:11], v[10:11], v[16:17] op_sel_hi:[1,0]
	v_pk_fma_f32 v[8:9], v[70:71], v[8:9], v[36:37]
	v_pk_mul_f32 v[6:7], v[6:7], v[16:17] op_sel_hi:[1,0]
	v_pk_fma_f32 v[4:5], v[74:75], v[4:5], v[40:41]
	v_pk_mul_f32 v[2:3], v[2:3], v[16:17] op_sel_hi:[1,0]
	v_pk_fma_f32 v[0:1], v[78:79], v[0:1], v[44:45]
	s_or_b64 s[40:41], vcc, s[40:41]
	global_store_dwordx2 v[14:15], v[12:13], off
	v_pk_fma_f32 v[10:11], v[68:69], v[10:11], v[38:39]
	v_cvt_pk_bf16_f32 v8, v8, v9
	v_pk_fma_f32 v[6:7], v[72:73], v[6:7], v[42:43]
	v_cvt_pk_bf16_f32 v9, v10, v11
	global_store_dwordx2 v[14:15], v[8:9], off offset:512
	v_cvt_pk_bf16_f32 v4, v4, v5
	v_cvt_pk_bf16_f32 v5, v6, v7
	global_store_dwordx2 v[14:15], v[4:5], off offset:1024
	v_pk_fma_f32 v[2:3], v[76:77], v[2:3], v[46:47]
	v_cvt_pk_bf16_f32 v0, v0, v1
	s_nop 0
	v_cvt_pk_bf16_f32 v1, v2, v3
	global_store_dwordx2 v[14:15], v[0:1], off offset:1536
	s_andn2_b64 exec, exec, s[40:41]
	s_cbranch_execnz .LBB0_138
